# S5 pass1 per-step LDS reads hoisted per sub-block (on top of norm/S5p2/attention changes)
# baseline (speedup 1.0000x reference)
.LBB0_1297:
	s_or_b64 exec, exec, s[0:1]
	v_mul_u32_u24_e32 v51, 0x210, v57
	v_lshlrev_b32_e32 v54, 2, v59
	v_lshlrev_b32_e32 v51, 2, v51
	v_lshl_add_u32 v50, v60, 2, v56
	s_waitcnt vmcnt(0) lgkmcnt(0)
	v_mfma_f32_16x16x32_bf16 v[60:63], v[44:47], v[8:11], 0
	v_add3_u32 v51, v56, v54, v51
	s_cmp_gt_i32 s4, 3
	s_cselect_b32 s0, 0x87, 3
	v_mfma_f32_16x16x32_bf16 v[54:57], v[44:47], v[0:3], 0
	s_nop 7
	ds_write2_b32 v51, v60, v54 offset1:16
	ds_write2_b32 v51, v61, v55 offset0:132 offset1:148
	v_add_u32_e32 v54, 0x400, v51
	ds_write2_b32 v54, v62, v56 offset0:8 offset1:24
	ds_write2_b32 v54, v63, v57 offset0:140 offset1:156
	v_mfma_f32_16x16x32_bf16 v[56:59], v[44:47], v[16:19], 0
	v_add_u32_e32 v55, 0xf0, v50
	s_addk_i32 s6, 0x84
	s_sub_i32 s0, s0, s4
	v_mfma_f32_16x16x32_bf16 v[60:63], v[44:47], v[4:7], 0
	s_nop 7
	ds_write2_b32 v51, v56, v60 offset0:32 offset1:48
	ds_write2_b32 v51, v57, v61 offset0:164 offset1:180
	ds_write2_b32 v54, v58, v62 offset0:40 offset1:56
	ds_write2_b32 v54, v59, v63 offset0:172 offset1:188
	v_mfma_f32_16x16x32_bf16 v[56:59], v[44:47], v[20:23], 0
	s_ashr_i32 s1, s6, 31
	s_add_u32 s0, s0, s6
	s_addc_u32 s1, 0, s1
	v_mfma_f32_16x16x32_bf16 v[60:63], v[44:47], v[12:15], 0
	s_nop 7
	ds_write2_b32 v51, v56, v60 offset0:64 offset1:80
	ds_write2_b32 v51, v57, v61 offset0:196 offset1:212
	ds_write2_b32 v54, v58, v62 offset0:72 offset1:88
	ds_write2_b32 v54, v59, v63 offset0:204 offset1:220
	v_mfma_f32_16x16x32_bf16 v[56:59], v[44:47], v[28:31], 0
	s_lshl_b64 s[0:1], s[0:1], 14
	v_mfma_f32_16x16x32_bf16 v[44:47], v[44:47], v[24:27], 0
	s_nop 7
	ds_write2_b32 v51, v56, v44 offset0:96 offset1:112
	ds_write2_b32 v51, v57, v45 offset0:228 offset1:244
	ds_write2_b32 v54, v58, v46 offset0:104 offset1:120
	ds_write2_b32 v54, v59, v47 offset0:236 offset1:252
	s_waitcnt vmcnt(0) lgkmcnt(0)
	ds_read2st64_b32 v[44:45], v55 offset0:30 offset1:31
	v_add_u32_e32 v84, 0xe0, v50
	ds_read2st64_b32 v[86:87], v84 offset0:28 offset1:29
	v_add_u32_e32 v85, 0xd0, v50
	ds_read2st64_b32 v[88:89], v85 offset0:26 offset1:27
	v_add_u32_e32 v90, 0xc0, v50
	ds_read2st64_b32 v[92:93], v90 offset0:24 offset1:25
	v_add_u32_e32 v91, 0xb0, v50
	ds_read2st64_b32 v[94:95], v91 offset0:22 offset1:23
	v_add_u32_e32 v96, 0xa0, v50
	ds_read2st64_b32 v[98:99], v96 offset0:20 offset1:21
	v_add_u32_e32 v97, 0x90, v50
	ds_read2st64_b32 v[100:101], v97 offset0:18 offset1:19
	v_add_u32_e32 v102, 0x80, v50
	ds_read2st64_b32 v[104:105], v102 offset0:16 offset1:17
	v_add_u32_e32 v103, 0x70, v50
	ds_read2st64_b32 v[106:107], v103 offset0:14 offset1:15
	v_add_u32_e32 v108, 0x60, v50
	ds_read2st64_b32 v[110:111], v108 offset0:12 offset1:13
	v_add_u32_e32 v109, 0x50, v50
	ds_read2st64_b32 v[112:113], v109 offset0:10 offset1:11
	v_add_u32_e32 v114, 64, v50
	ds_read2st64_b32 v[116:117], v114 offset0:8 offset1:9
	v_pk_mul_f32 v[46:47], v[52:53], 0 op_sel_hi:[1,0]
	s_nop 0
	v_sub_f32_e32 v56, v46, v47
	s_waitcnt lgkmcnt(0)
	v_add_f32_e32 v56, v56, v44
	v_add_f32_e32 v44, v46, v47
	v_add_f32_e32 v46, v44, v45
	v_add_u32_e32 v44, 0xe0, v50
	v_add_u32_e32 v45, 0xd0, v50
	v_pk_mul_f32 v[46:47], v[52:53], v[46:47] op_sel:[1,0] op_sel_hi:[0,0]
	v_pk_fma_f32 v[62:63], v[52:53], v[56:57], v[46:47] neg_lo:[0,0,1] neg_hi:[0,0,1]
	v_pk_fma_f32 v[46:47], v[52:53], v[56:57], v[46:47] op_sel_hi:[1,0,1]
	s_nop 0
	v_mov_b32_e32 v63, v47
	s_waitcnt lgkmcnt(1)
	v_pk_add_f32 v[46:47], v[86:87], v[62:63]
	s_nop 0
	v_pk_mul_f32 v[56:57], v[52:53], v[46:47]
	v_pk_mul_f32 v[46:47], v[52:53], v[46:47] op_sel:[1,0] op_sel_hi:[0,1]
	v_add_f32_e32 v46, v46, v47
	v_sub_f32_e32 v56, v56, v57
	s_waitcnt lgkmcnt(0)
	v_add_f32_e32 v58, v89, v46
	v_add_u32_e32 v46, 0xc0, v50
	v_add_f32_e32 v56, v88, v56
	v_add_u32_e32 v47, 0xb0, v50
	v_mov_b32_e32 v59, v87
	v_pk_mul_f32 v[58:59], v[52:53], v[58:59] op_sel:[1,0] op_sel_hi:[0,0]
	v_pk_fma_f32 v[64:65], v[52:53], v[56:57], v[58:59] neg_lo:[0,0,1] neg_hi:[0,0,1]
	v_pk_fma_f32 v[56:57], v[52:53], v[56:57], v[58:59] op_sel_hi:[1,0,1]
	s_nop 0
	v_mov_b32_e32 v65, v57
	s_waitcnt lgkmcnt(1)
	v_pk_add_f32 v[56:57], v[92:93], v[64:65]
	s_nop 0
	v_pk_mul_f32 v[58:59], v[52:53], v[56:57]
	v_pk_mul_f32 v[56:57], v[52:53], v[56:57] op_sel:[1,0] op_sel_hi:[0,1]
	v_add_f32_e32 v56, v56, v57
	v_sub_f32_e32 v58, v58, v59
	s_waitcnt lgkmcnt(0)
	v_add_f32_e32 v60, v95, v56
	v_add_u32_e32 v56, 0xa0, v50
	v_add_f32_e32 v58, v94, v58
	v_add_u32_e32 v57, 0x90, v50
	v_mov_b32_e32 v61, v93
	v_pk_mul_f32 v[60:61], v[52:53], v[60:61] op_sel:[1,0] op_sel_hi:[0,0]
	v_pk_fma_f32 v[66:67], v[52:53], v[58:59], v[60:61] neg_lo:[0,0,1] neg_hi:[0,0,1]
	v_pk_fma_f32 v[58:59], v[52:53], v[58:59], v[60:61] op_sel_hi:[1,0,1]
	s_nop 0
	v_mov_b32_e32 v67, v59
	s_waitcnt lgkmcnt(1)
	v_pk_add_f32 v[58:59], v[98:99], v[66:67]
	s_nop 0
	v_pk_mul_f32 v[60:61], v[52:53], v[58:59]
	v_pk_mul_f32 v[58:59], v[52:53], v[58:59] op_sel:[1,0] op_sel_hi:[0,1]
	v_add_f32_e32 v58, v58, v59
	v_sub_f32_e32 v60, v60, v61
	s_waitcnt lgkmcnt(0)
	v_add_f32_e32 v62, v101, v58
	v_add_u32_e32 v58, 0x80, v50
	v_add_f32_e32 v60, v100, v60
	v_add_u32_e32 v59, 0x70, v50
	v_mov_b32_e32 v63, v99
	v_pk_mul_f32 v[62:63], v[52:53], v[62:63] op_sel:[1,0] op_sel_hi:[0,0]
	v_pk_fma_f32 v[68:69], v[52:53], v[60:61], v[62:63] neg_lo:[0,0,1] neg_hi:[0,0,1]
	v_pk_fma_f32 v[60:61], v[52:53], v[60:61], v[62:63] op_sel_hi:[1,0,1]
	s_nop 0
	v_mov_b32_e32 v69, v61
	s_waitcnt lgkmcnt(1)
	v_pk_add_f32 v[60:61], v[104:105], v[68:69]
	s_nop 0
	v_pk_mul_f32 v[62:63], v[52:53], v[60:61]
	v_pk_mul_f32 v[60:61], v[52:53], v[60:61] op_sel:[1,0] op_sel_hi:[0,1]
	v_add_f32_e32 v60, v60, v61
	v_sub_f32_e32 v62, v62, v63
	s_waitcnt lgkmcnt(0)
	v_add_f32_e32 v64, v107, v60
	v_add_u32_e32 v60, 0x60, v50
	v_add_f32_e32 v62, v106, v62
	v_add_u32_e32 v61, 0x50, v50
	v_mov_b32_e32 v65, v105
	v_pk_mul_f32 v[64:65], v[52:53], v[64:65] op_sel:[1,0] op_sel_hi:[0,0]
	v_pk_fma_f32 v[70:71], v[52:53], v[62:63], v[64:65] neg_lo:[0,0,1] neg_hi:[0,0,1]
	v_pk_fma_f32 v[62:63], v[52:53], v[62:63], v[64:65] op_sel_hi:[1,0,1]
	s_nop 0
	v_mov_b32_e32 v71, v63
	s_waitcnt lgkmcnt(1)
	v_pk_add_f32 v[62:63], v[110:111], v[70:71]
	s_nop 0
	v_pk_mul_f32 v[64:65], v[52:53], v[62:63]
	v_pk_mul_f32 v[62:63], v[52:53], v[62:63] op_sel:[1,0] op_sel_hi:[0,1]
	v_add_f32_e32 v62, v62, v63
	v_sub_f32_e32 v64, v64, v65
	s_waitcnt lgkmcnt(0)
	v_add_f32_e32 v66, v113, v62
	v_add_u32_e32 v62, 64, v50
	v_add_f32_e32 v64, v112, v64
	v_add_u32_e32 v63, 48, v50
	v_mov_b32_e32 v67, v111
	v_pk_mul_f32 v[66:67], v[52:53], v[66:67] op_sel:[1,0] op_sel_hi:[0,0]
	ds_read2st64_b32 v[70:71], v63 offset0:6 offset1:7
	v_pk_fma_f32 v[72:73], v[52:53], v[64:65], v[66:67] neg_lo:[0,0,1] neg_hi:[0,0,1]
	v_pk_fma_f32 v[64:65], v[52:53], v[64:65], v[66:67] op_sel_hi:[1,0,1]
	s_nop 0
	v_mov_b32_e32 v73, v65
	s_waitcnt lgkmcnt(1)
	v_pk_add_f32 v[64:65], v[116:117], v[72:73]
	s_nop 0
	v_pk_mul_f32 v[66:67], v[52:53], v[64:65]
	v_pk_mul_f32 v[64:65], v[52:53], v[64:65] op_sel:[1,0] op_sel_hi:[0,1]
	v_add_f32_e32 v64, v64, v65
	v_sub_f32_e32 v66, v66, v67
	s_waitcnt lgkmcnt(0)
	v_add_f32_e32 v68, v71, v64
	v_add_u32_e32 v64, 32, v50
	v_add_f32_e32 v66, v70, v66
	ds_read2st64_b32 v[70:71], v64 offset0:4 offset1:5
	ds_read2_b32 v[72:73], v50 offset0:132 offset1:196
	v_mov_b32_e32 v69, v117
	v_pk_mul_f32 v[68:69], v[52:53], v[68:69] op_sel:[1,0] op_sel_hi:[0,0]
	v_pk_fma_f32 v[74:75], v[52:53], v[66:67], v[68:69] neg_lo:[0,0,1] neg_hi:[0,0,1]
	v_pk_fma_f32 v[66:67], v[52:53], v[66:67], v[68:69] op_sel_hi:[1,0,1]
	ds_read2st64_b32 v[78:79], v50 offset1:1
	v_mov_b32_e32 v75, v67
	s_waitcnt lgkmcnt(2)
	v_pk_add_f32 v[66:67], v[70:71], v[74:75]
	s_waitcnt vmcnt(0) lgkmcnt(0)
	s_nop 0
	v_pk_mul_f32 v[68:69], v[52:53], v[66:67]
	v_pk_mul_f32 v[66:67], v[52:53], v[66:67] op_sel:[1,0] op_sel_hi:[0,1]
	v_sub_f32_e32 v65, v68, v69
	s_waitcnt lgkmcnt(1)
	v_add_f32_e32 v74, v72, v65
	v_add_f32_e32 v65, v66, v67
	v_add_f32_e32 v76, v73, v65
	v_mfma_f32_16x16x32_bf16 v[66:69], v[40:43], v[8:11], 0
	v_mfma_f32_16x16x32_bf16 v[70:73], v[40:43], v[0:3], 0
	s_nop 7
	ds_write2_b32 v51, v66, v70 offset1:16
	ds_write2_b32 v51, v67, v71 offset0:132 offset1:148
	ds_write2_b32 v54, v68, v72 offset0:8 offset1:24
	ds_write2_b32 v54, v69, v73 offset0:140 offset1:156
	v_mfma_f32_16x16x32_bf16 v[66:69], v[40:43], v[16:19], 0
	v_mfma_f32_16x16x32_bf16 v[70:73], v[40:43], v[4:7], 0
	s_nop 7
	ds_write2_b32 v51, v66, v70 offset0:32 offset1:48
	ds_write2_b32 v51, v67, v71 offset0:164 offset1:180
	ds_write2_b32 v54, v68, v72 offset0:40 offset1:56
	ds_write2_b32 v54, v69, v73 offset0:172 offset1:188
	v_mfma_f32_16x16x32_bf16 v[66:69], v[40:43], v[20:23], 0
	v_mfma_f32_16x16x32_bf16 v[70:73], v[40:43], v[12:15], 0
	s_nop 7
	ds_write2_b32 v51, v66, v70 offset0:64 offset1:80
	ds_write2_b32 v51, v67, v71 offset0:196 offset1:212
	ds_write2_b32 v54, v68, v72 offset0:72 offset1:88
	ds_write2_b32 v54, v69, v73 offset0:204 offset1:220
	v_mfma_f32_16x16x32_bf16 v[66:69], v[40:43], v[28:31], 0
	v_mfma_f32_16x16x32_bf16 v[40:43], v[40:43], v[24:27], 0
	s_nop 7
	ds_write2_b32 v51, v66, v40 offset0:96 offset1:112
	ds_write2_b32 v51, v67, v41 offset0:228 offset1:244
	ds_write2_b32 v54, v68, v42 offset0:104 offset1:120
	ds_write2_b32 v54, v69, v43 offset0:236 offset1:252
	v_pk_mul_f32 v[42:43], v[52:53], v[76:77] op_sel:[1,0] op_sel_hi:[0,0]
	s_waitcnt vmcnt(0) lgkmcnt(0)
	ds_read2st64_b32 v[40:41], v55 offset0:30 offset1:31
	ds_read2st64_b32 v[84:85], v44 offset0:28 offset1:29
	ds_read2st64_b32 v[86:87], v45 offset0:26 offset1:27
	ds_read2st64_b32 v[88:89], v46 offset0:24 offset1:25
	ds_read2st64_b32 v[90:91], v47 offset0:22 offset1:23
	ds_read2st64_b32 v[92:93], v56 offset0:20 offset1:21
	ds_read2st64_b32 v[94:95], v57 offset0:18 offset1:19
	ds_read2st64_b32 v[96:97], v58 offset0:16 offset1:17
	ds_read2st64_b32 v[98:99], v59 offset0:14 offset1:15
	ds_read2st64_b32 v[100:101], v60 offset0:12 offset1:13
	ds_read2st64_b32 v[102:103], v61 offset0:10 offset1:11
	ds_read2st64_b32 v[104:105], v62 offset0:8 offset1:9
	v_pk_fma_f32 v[66:67], v[52:53], v[74:75], v[42:43] neg_lo:[0,0,1] neg_hi:[0,0,1]
	v_pk_fma_f32 v[42:43], v[52:53], v[74:75], v[42:43] op_sel_hi:[1,0,1]
	s_nop 0
	v_mov_b32_e32 v67, v43
	s_waitcnt lgkmcnt(14)
	v_pk_add_f32 v[42:43], v[78:79], v[66:67]
	s_nop 0
	v_pk_mul_f32 v[66:67], v[52:53], v[42:43]
	v_pk_mul_f32 v[42:43], v[52:53], v[42:43] op_sel:[1,0] op_sel_hi:[0,1]
	v_add_f32_e32 v42, v42, v43
	v_sub_f32_e32 v65, v66, v67
	s_waitcnt lgkmcnt(0)
	v_add_f32_e32 v42, v42, v41
	v_add_f32_e32 v40, v65, v40
	v_pk_mul_f32 v[42:43], v[52:53], v[42:43] op_sel:[1,0] op_sel_hi:[0,0]
	v_pk_fma_f32 v[70:71], v[52:53], v[40:41], v[42:43] neg_lo:[0,0,1] neg_hi:[0,0,1]
	v_pk_fma_f32 v[40:41], v[52:53], v[40:41], v[42:43] op_sel_hi:[1,0,1]
	s_nop 0
	v_mov_b32_e32 v71, v41
	s_waitcnt lgkmcnt(1)
	v_pk_add_f32 v[40:41], v[84:85], v[70:71]
	s_nop 0
	v_pk_mul_f32 v[42:43], v[52:53], v[40:41]
	v_pk_mul_f32 v[40:41], v[52:53], v[40:41] op_sel:[1,0] op_sel_hi:[0,1]
	v_sub_f32_e32 v42, v42, v43
	v_add_f32_e32 v40, v40, v41
	s_waitcnt lgkmcnt(0)
	v_add_f32_e32 v42, v86, v42
	v_add_f32_e32 v40, v87, v40
	v_pk_mul_f32 v[40:41], v[52:53], v[40:41] op_sel:[1,0] op_sel_hi:[0,0]
	v_pk_fma_f32 v[70:71], v[52:53], v[42:43], v[40:41] neg_lo:[0,0,1] neg_hi:[0,0,1]
	v_pk_fma_f32 v[40:41], v[52:53], v[42:43], v[40:41] op_sel_hi:[1,0,1]
	s_nop 0
	v_mov_b32_e32 v71, v41
	s_waitcnt lgkmcnt(1)
	v_pk_add_f32 v[40:41], v[88:89], v[70:71]
	s_nop 0
	v_pk_mul_f32 v[42:43], v[52:53], v[40:41]
	v_pk_mul_f32 v[40:41], v[52:53], v[40:41] op_sel:[1,0] op_sel_hi:[0,1]
	v_sub_f32_e32 v42, v42, v43
	v_add_f32_e32 v40, v40, v41
	s_waitcnt lgkmcnt(0)
	v_add_f32_e32 v42, v90, v42
	v_add_f32_e32 v40, v91, v40
	v_pk_mul_f32 v[40:41], v[52:53], v[40:41] op_sel:[1,0] op_sel_hi:[0,0]
	v_pk_fma_f32 v[70:71], v[52:53], v[42:43], v[40:41] neg_lo:[0,0,1] neg_hi:[0,0,1]
	v_pk_fma_f32 v[40:41], v[52:53], v[42:43], v[40:41] op_sel_hi:[1,0,1]
	s_nop 0
	v_mov_b32_e32 v71, v41
	s_waitcnt lgkmcnt(1)
	v_pk_add_f32 v[40:41], v[92:93], v[70:71]
	s_nop 0
	v_pk_mul_f32 v[42:43], v[52:53], v[40:41]
	v_pk_mul_f32 v[40:41], v[52:53], v[40:41] op_sel:[1,0] op_sel_hi:[0,1]
	v_sub_f32_e32 v42, v42, v43
	v_add_f32_e32 v40, v40, v41
	s_waitcnt lgkmcnt(0)
	v_add_f32_e32 v42, v94, v42
	v_add_f32_e32 v40, v95, v40
	v_pk_mul_f32 v[40:41], v[52:53], v[40:41] op_sel:[1,0] op_sel_hi:[0,0]
	v_pk_fma_f32 v[70:71], v[52:53], v[42:43], v[40:41] neg_lo:[0,0,1] neg_hi:[0,0,1]
	v_pk_fma_f32 v[40:41], v[52:53], v[42:43], v[40:41] op_sel_hi:[1,0,1]
	s_nop 0
	v_mov_b32_e32 v71, v41
	s_waitcnt lgkmcnt(1)
	v_pk_add_f32 v[40:41], v[96:97], v[70:71]
	s_nop 0
	v_pk_mul_f32 v[42:43], v[52:53], v[40:41]
	v_pk_mul_f32 v[40:41], v[52:53], v[40:41] op_sel:[1,0] op_sel_hi:[0,1]
	v_sub_f32_e32 v42, v42, v43
	v_add_f32_e32 v40, v40, v41
	s_waitcnt lgkmcnt(0)
	v_add_f32_e32 v42, v98, v42
	v_add_f32_e32 v40, v99, v40
	v_pk_mul_f32 v[40:41], v[52:53], v[40:41] op_sel:[1,0] op_sel_hi:[0,0]
	v_pk_fma_f32 v[70:71], v[52:53], v[42:43], v[40:41] neg_lo:[0,0,1] neg_hi:[0,0,1]
	v_pk_fma_f32 v[40:41], v[52:53], v[42:43], v[40:41] op_sel_hi:[1,0,1]
	s_nop 0
	v_mov_b32_e32 v71, v41
	s_waitcnt lgkmcnt(1)
	v_pk_add_f32 v[40:41], v[100:101], v[70:71]
	s_nop 0
	v_pk_mul_f32 v[42:43], v[52:53], v[40:41]
	v_pk_mul_f32 v[40:41], v[52:53], v[40:41] op_sel:[1,0] op_sel_hi:[0,1]
	v_sub_f32_e32 v42, v42, v43
	v_add_f32_e32 v40, v40, v41
	s_waitcnt lgkmcnt(0)
	v_add_f32_e32 v42, v102, v42
	v_add_f32_e32 v40, v103, v40
	ds_read2st64_b32 v[68:69], v63 offset0:6 offset1:7
	v_pk_mul_f32 v[40:41], v[52:53], v[40:41] op_sel:[1,0] op_sel_hi:[0,0]
	v_pk_fma_f32 v[70:71], v[52:53], v[42:43], v[40:41] neg_lo:[0,0,1] neg_hi:[0,0,1]
	v_pk_fma_f32 v[40:41], v[52:53], v[42:43], v[40:41] op_sel_hi:[1,0,1]
	s_nop 0
	v_mov_b32_e32 v71, v41
	s_waitcnt lgkmcnt(1)
	v_pk_add_f32 v[40:41], v[104:105], v[70:71]
	s_nop 0
	v_pk_mul_f32 v[42:43], v[52:53], v[40:41]
	v_pk_mul_f32 v[40:41], v[52:53], v[40:41] op_sel:[1,0] op_sel_hi:[0,1]
	v_sub_f32_e32 v42, v42, v43
	v_add_f32_e32 v40, v40, v41
	s_waitcnt lgkmcnt(0)
	v_add_f32_e32 v42, v68, v42
	v_add_f32_e32 v40, v69, v40
	ds_read2st64_b32 v[66:67], v64 offset0:4 offset1:5
	ds_read2_b32 v[68:69], v50 offset0:132 offset1:196
	v_pk_mul_f32 v[40:41], v[52:53], v[40:41] op_sel:[1,0] op_sel_hi:[0,0]
	v_pk_fma_f32 v[70:71], v[52:53], v[42:43], v[40:41] neg_lo:[0,0,1] neg_hi:[0,0,1]
	v_pk_fma_f32 v[40:41], v[52:53], v[42:43], v[40:41] op_sel_hi:[1,0,1]
	ds_read2st64_b32 v[74:75], v50 offset1:1
	v_mov_b32_e32 v71, v41
	s_waitcnt lgkmcnt(2)
	v_pk_add_f32 v[40:41], v[66:67], v[70:71]
	s_waitcnt vmcnt(0) lgkmcnt(0)
	s_nop 0
	v_pk_mul_f32 v[42:43], v[52:53], v[40:41]
	v_pk_mul_f32 v[40:41], v[52:53], v[40:41] op_sel:[1,0] op_sel_hi:[0,1]
	v_sub_f32_e32 v42, v42, v43
	v_add_f32_e32 v40, v40, v41
	s_waitcnt lgkmcnt(1)
	v_add_f32_e32 v70, v68, v42
	v_add_f32_e32 v72, v69, v40
	v_mfma_f32_16x16x32_bf16 v[40:43], v[36:39], v[8:11], 0
	v_mfma_f32_16x16x32_bf16 v[66:69], v[36:39], v[0:3], 0
	s_nop 7
	ds_write2_b32 v51, v40, v66 offset1:16
	ds_write2_b32 v51, v41, v67 offset0:132 offset1:148
	ds_write2_b32 v54, v42, v68 offset0:8 offset1:24
	ds_write2_b32 v54, v43, v69 offset0:140 offset1:156
	v_mfma_f32_16x16x32_bf16 v[40:43], v[36:39], v[16:19], 0
	v_mfma_f32_16x16x32_bf16 v[66:69], v[36:39], v[4:7], 0
	s_nop 7
	ds_write2_b32 v51, v40, v66 offset0:32 offset1:48
	ds_write2_b32 v51, v41, v67 offset0:164 offset1:180
	ds_write2_b32 v54, v42, v68 offset0:40 offset1:56
	ds_write2_b32 v54, v43, v69 offset0:172 offset1:188
	v_mfma_f32_16x16x32_bf16 v[40:43], v[36:39], v[20:23], 0
	v_mfma_f32_16x16x32_bf16 v[66:69], v[36:39], v[12:15], 0
	s_nop 7
	ds_write2_b32 v51, v40, v66 offset0:64 offset1:80
	ds_write2_b32 v51, v41, v67 offset0:196 offset1:212
	ds_write2_b32 v54, v42, v68 offset0:72 offset1:88
	ds_write2_b32 v54, v43, v69 offset0:204 offset1:220
	v_mfma_f32_16x16x32_bf16 v[40:43], v[36:39], v[28:31], 0
	v_mfma_f32_16x16x32_bf16 v[36:39], v[36:39], v[24:27], 0
	s_nop 7
	ds_write2_b32 v51, v40, v36 offset0:96 offset1:112
	ds_write2_b32 v51, v41, v37 offset0:228 offset1:244
	ds_write2_b32 v54, v42, v38 offset0:104 offset1:120
	ds_write2_b32 v54, v43, v39 offset0:236 offset1:252
	v_pk_mul_f32 v[38:39], v[52:53], v[72:73] op_sel:[1,0] op_sel_hi:[0,0]
	s_waitcnt vmcnt(0) lgkmcnt(0)
	ds_read2st64_b32 v[36:37], v55 offset0:30 offset1:31
	ds_read2st64_b32 v[84:85], v44 offset0:28 offset1:29
	ds_read2st64_b32 v[86:87], v45 offset0:26 offset1:27
	ds_read2st64_b32 v[88:89], v46 offset0:24 offset1:25
	ds_read2st64_b32 v[90:91], v47 offset0:22 offset1:23
	ds_read2st64_b32 v[92:93], v56 offset0:20 offset1:21
	ds_read2st64_b32 v[94:95], v57 offset0:18 offset1:19
	ds_read2st64_b32 v[96:97], v58 offset0:16 offset1:17
	ds_read2st64_b32 v[98:99], v59 offset0:14 offset1:15
	ds_read2st64_b32 v[100:101], v60 offset0:12 offset1:13
	ds_read2st64_b32 v[102:103], v61 offset0:10 offset1:11
	ds_read2st64_b32 v[104:105], v62 offset0:8 offset1:9
	v_pk_fma_f32 v[40:41], v[52:53], v[70:71], v[38:39] neg_lo:[0,0,1] neg_hi:[0,0,1]
	v_pk_fma_f32 v[38:39], v[52:53], v[70:71], v[38:39] op_sel_hi:[1,0,1]
	v_mfma_f32_16x16x32_bf16 v[8:11], v[32:35], v[8:11], 0
	v_mov_b32_e32 v41, v39
	s_waitcnt lgkmcnt(14)
	v_pk_add_f32 v[38:39], v[74:75], v[40:41]
	s_nop 0
	v_pk_mul_f32 v[40:41], v[52:53], v[38:39]
	v_pk_mul_f32 v[38:39], v[52:53], v[38:39] op_sel:[1,0] op_sel_hi:[0,1]
	v_sub_f32_e32 v40, v40, v41
	v_add_f32_e32 v38, v38, v39
	s_waitcnt lgkmcnt(0)
	v_add_f32_e32 v36, v40, v36
	v_add_f32_e32 v38, v38, v37
	v_pk_mul_f32 v[38:39], v[52:53], v[38:39] op_sel:[1,0] op_sel_hi:[0,0]
	v_pk_fma_f32 v[66:67], v[52:53], v[36:37], v[38:39] neg_lo:[0,0,1] neg_hi:[0,0,1]
	v_pk_fma_f32 v[36:37], v[52:53], v[36:37], v[38:39] op_sel_hi:[1,0,1]
	v_mfma_f32_16x16x32_bf16 v[0:3], v[32:35], v[0:3], 0
	v_mov_b32_e32 v67, v37
	s_waitcnt lgkmcnt(1)
	v_pk_add_f32 v[36:37], v[84:85], v[66:67]
	s_nop 0
	v_pk_mul_f32 v[38:39], v[52:53], v[36:37]
	v_pk_mul_f32 v[36:37], v[52:53], v[36:37] op_sel:[1,0] op_sel_hi:[0,1]
	v_sub_f32_e32 v38, v38, v39
	v_add_f32_e32 v36, v36, v37
	s_waitcnt lgkmcnt(0)
	v_add_f32_e32 v38, v86, v38
	v_add_f32_e32 v36, v87, v36
	v_pk_mul_f32 v[36:37], v[52:53], v[36:37] op_sel:[1,0] op_sel_hi:[0,0]
	v_pk_fma_f32 v[66:67], v[52:53], v[38:39], v[36:37] neg_lo:[0,0,1] neg_hi:[0,0,1]
	v_pk_fma_f32 v[36:37], v[52:53], v[38:39], v[36:37] op_sel_hi:[1,0,1]
	v_mfma_f32_16x16x32_bf16 v[4:7], v[32:35], v[4:7], 0
	v_mov_b32_e32 v67, v37
	s_waitcnt lgkmcnt(1)
	v_pk_add_f32 v[36:37], v[88:89], v[66:67]
	s_nop 0
	v_pk_mul_f32 v[38:39], v[52:53], v[36:37]
	v_pk_mul_f32 v[36:37], v[52:53], v[36:37] op_sel:[1,0] op_sel_hi:[0,1]
	v_sub_f32_e32 v38, v38, v39
	v_add_f32_e32 v36, v36, v37
	s_waitcnt lgkmcnt(0)
	v_add_f32_e32 v38, v90, v38
	v_add_f32_e32 v36, v91, v36
	v_pk_mul_f32 v[36:37], v[52:53], v[36:37] op_sel:[1,0] op_sel_hi:[0,0]
	v_pk_fma_f32 v[66:67], v[52:53], v[38:39], v[36:37] neg_lo:[0,0,1] neg_hi:[0,0,1]
	v_pk_fma_f32 v[36:37], v[52:53], v[38:39], v[36:37] op_sel_hi:[1,0,1]
	s_nop 0
	v_mov_b32_e32 v67, v37
	s_waitcnt lgkmcnt(1)
	v_pk_add_f32 v[36:37], v[92:93], v[66:67]
	s_nop 0
	v_pk_mul_f32 v[38:39], v[52:53], v[36:37]
	v_pk_mul_f32 v[36:37], v[52:53], v[36:37] op_sel:[1,0] op_sel_hi:[0,1]
	v_sub_f32_e32 v38, v38, v39
	v_add_f32_e32 v36, v36, v37
	s_waitcnt lgkmcnt(0)
	v_add_f32_e32 v38, v94, v38
	v_add_f32_e32 v36, v95, v36
	v_pk_mul_f32 v[36:37], v[52:53], v[36:37] op_sel:[1,0] op_sel_hi:[0,0]
	v_pk_fma_f32 v[66:67], v[52:53], v[38:39], v[36:37] neg_lo:[0,0,1] neg_hi:[0,0,1]
	v_pk_fma_f32 v[36:37], v[52:53], v[38:39], v[36:37] op_sel_hi:[1,0,1]
	s_nop 0
	v_mov_b32_e32 v67, v37
	s_waitcnt lgkmcnt(1)
	v_pk_add_f32 v[36:37], v[96:97], v[66:67]
	s_nop 0
	v_pk_mul_f32 v[38:39], v[52:53], v[36:37]
	v_pk_mul_f32 v[36:37], v[52:53], v[36:37] op_sel:[1,0] op_sel_hi:[0,1]
	v_sub_f32_e32 v38, v38, v39
	v_add_f32_e32 v36, v36, v37
	s_waitcnt lgkmcnt(0)
	v_add_f32_e32 v38, v98, v38
	v_add_f32_e32 v36, v99, v36
	v_pk_mul_f32 v[36:37], v[52:53], v[36:37] op_sel:[1,0] op_sel_hi:[0,0]
	v_pk_fma_f32 v[66:67], v[52:53], v[38:39], v[36:37] neg_lo:[0,0,1] neg_hi:[0,0,1]
	v_pk_fma_f32 v[36:37], v[52:53], v[38:39], v[36:37] op_sel_hi:[1,0,1]
	s_nop 0
	v_mov_b32_e32 v67, v37
	s_waitcnt lgkmcnt(1)
	v_pk_add_f32 v[36:37], v[100:101], v[66:67]
	s_nop 0
	v_pk_mul_f32 v[38:39], v[52:53], v[36:37]
	v_pk_mul_f32 v[36:37], v[52:53], v[36:37] op_sel:[1,0] op_sel_hi:[0,1]
	v_sub_f32_e32 v38, v38, v39
	v_add_f32_e32 v36, v36, v37
	s_waitcnt lgkmcnt(0)
	v_add_f32_e32 v38, v102, v38
	v_add_f32_e32 v36, v103, v36
	ds_read2st64_b32 v[42:43], v63 offset0:6 offset1:7
	v_pk_mul_f32 v[36:37], v[52:53], v[36:37] op_sel:[1,0] op_sel_hi:[0,0]
	v_pk_fma_f32 v[66:67], v[52:53], v[38:39], v[36:37] neg_lo:[0,0,1] neg_hi:[0,0,1]
	v_pk_fma_f32 v[36:37], v[52:53], v[38:39], v[36:37] op_sel_hi:[1,0,1]
	s_nop 0
	v_mov_b32_e32 v67, v37
	s_waitcnt lgkmcnt(1)
	v_pk_add_f32 v[36:37], v[104:105], v[66:67]
	s_nop 0
	v_pk_mul_f32 v[38:39], v[52:53], v[36:37]
	v_pk_mul_f32 v[36:37], v[52:53], v[36:37] op_sel:[1,0] op_sel_hi:[0,1]
	v_sub_f32_e32 v38, v38, v39
	v_add_f32_e32 v36, v36, v37
	s_waitcnt lgkmcnt(0)
	v_add_f32_e32 v38, v42, v38
	v_add_f32_e32 v36, v43, v36
	ds_read2st64_b32 v[40:41], v64 offset0:4 offset1:5
	ds_read2_b32 v[42:43], v50 offset0:132 offset1:196
	v_pk_mul_f32 v[36:37], v[52:53], v[36:37] op_sel:[1,0] op_sel_hi:[0,0]
	v_pk_fma_f32 v[66:67], v[52:53], v[38:39], v[36:37] neg_lo:[0,0,1] neg_hi:[0,0,1]
	v_pk_fma_f32 v[36:37], v[52:53], v[38:39], v[36:37] op_sel_hi:[1,0,1]
	s_nop 0
	v_mov_b32_e32 v67, v37
	s_waitcnt lgkmcnt(1)
	v_pk_add_f32 v[36:37], v[40:41], v[66:67]
	ds_read2st64_b32 v[40:41], v50 offset1:1
	s_waitcnt vmcnt(0) lgkmcnt(0)
	ds_write2_b32 v51, v8, v0 offset1:16
	ds_write2_b32 v51, v9, v1 offset0:132 offset1:148
	ds_write2_b32 v54, v10, v2 offset0:8 offset1:24
	ds_write2_b32 v54, v11, v3 offset0:140 offset1:156
	v_mfma_f32_16x16x32_bf16 v[0:3], v[32:35], v[16:19], 0
	s_nop 7
	ds_write2_b32 v51, v0, v4 offset0:32 offset1:48
	ds_write2_b32 v51, v1, v5 offset0:164 offset1:180
	ds_write2_b32 v54, v2, v6 offset0:40 offset1:56
	ds_write2_b32 v54, v3, v7 offset0:172 offset1:188
	v_mfma_f32_16x16x32_bf16 v[0:3], v[32:35], v[20:23], 0
	v_mul_f32_e64 v38, v52, v36
	v_mul_f32_e64 v39, v53, v37
	v_pk_mul_f32 v[36:37], v[52:53], v[36:37] op_sel:[1,0] op_sel_hi:[0,1]
	v_add_f32_e32 v36, v36, v37
	v_mfma_f32_16x16x32_bf16 v[4:7], v[32:35], v[12:15], 0
	s_nop 7
	ds_write2_b32 v51, v0, v4 offset0:64 offset1:80
	ds_write2_b32 v51, v1, v5 offset0:196 offset1:212
	ds_write2_b32 v54, v2, v6 offset0:72 offset1:88
	ds_write2_b32 v54, v3, v7 offset0:204 offset1:220
	v_mfma_f32_16x16x32_bf16 v[0:3], v[32:35], v[28:31], 0
	v_sub_f32_e32 v38, v38, v39
	s_waitcnt lgkmcnt(13)
	v_add_f32_e32 v36, v43, v36
	v_add_f32_e32 v38, v42, v38
	v_mfma_f32_16x16x32_bf16 v[4:7], v[32:35], v[24:27], 0
	s_nop 7
	ds_write2_b32 v51, v0, v4 offset0:96 offset1:112
	ds_write2_b32 v51, v1, v5 offset0:228 offset1:244
	ds_write2_b32 v54, v2, v6 offset0:104 offset1:120
	ds_write2_b32 v54, v3, v7 offset0:236 offset1:252
	v_pk_mul_f32 v[2:3], v[52:53], v[36:37] op_sel:[1,0] op_sel_hi:[0,0]
	s_waitcnt vmcnt(0) lgkmcnt(0)
	ds_read2st64_b32 v[0:1], v55 offset0:30 offset1:31
	ds_read2st64_b32 v[84:85], v44 offset0:28 offset1:29
	ds_read2st64_b32 v[86:87], v45 offset0:26 offset1:27
	ds_read2st64_b32 v[88:89], v46 offset0:24 offset1:25
	ds_read2st64_b32 v[90:91], v47 offset0:22 offset1:23
	ds_read2st64_b32 v[92:93], v56 offset0:20 offset1:21
	ds_read2st64_b32 v[94:95], v57 offset0:18 offset1:19
	ds_read2st64_b32 v[96:97], v58 offset0:16 offset1:17
	ds_read2st64_b32 v[98:99], v59 offset0:14 offset1:15
	ds_read2st64_b32 v[100:101], v60 offset0:12 offset1:13
	ds_read2st64_b32 v[102:103], v61 offset0:10 offset1:11
	ds_read2st64_b32 v[104:105], v62 offset0:8 offset1:9
	v_pk_fma_f32 v[4:5], v[52:53], v[38:39], v[2:3] neg_lo:[0,0,1] neg_hi:[0,0,1]
	v_pk_fma_f32 v[2:3], v[52:53], v[38:39], v[2:3] op_sel_hi:[1,0,1]
	s_nop 0
	v_mov_b32_e32 v5, v3
	s_waitcnt lgkmcnt(14)
	v_pk_add_f32 v[2:3], v[40:41], v[4:5]
	s_nop 0
	v_pk_mul_f32 v[4:5], v[52:53], v[2:3]
	v_pk_mul_f32 v[2:3], v[52:53], v[2:3] op_sel:[1,0] op_sel_hi:[0,1]
	v_sub_f32_e32 v4, v4, v5
	v_add_f32_e32 v2, v2, v3
	s_waitcnt lgkmcnt(0)
	v_add_f32_e32 v0, v4, v0
	v_add_f32_e32 v2, v2, v1
	v_pk_mul_f32 v[2:3], v[52:53], v[2:3] op_sel:[1,0] op_sel_hi:[0,0]
	v_pk_fma_f32 v[8:9], v[52:53], v[0:1], v[2:3] neg_lo:[0,0,1] neg_hi:[0,0,1]
	v_pk_fma_f32 v[0:1], v[52:53], v[0:1], v[2:3] op_sel_hi:[1,0,1]
	s_nop 0
	v_mov_b32_e32 v9, v1
	s_waitcnt lgkmcnt(1)
	v_pk_add_f32 v[0:1], v[84:85], v[8:9]
	s_nop 0
	v_pk_mul_f32 v[2:3], v[52:53], v[0:1]
	v_pk_mul_f32 v[0:1], v[52:53], v[0:1] op_sel:[1,0] op_sel_hi:[0,1]
	v_sub_f32_e32 v2, v2, v3
	v_add_f32_e32 v0, v0, v1
	s_waitcnt lgkmcnt(0)
	v_add_f32_e32 v2, v86, v2
	v_add_f32_e32 v0, v87, v0
	v_pk_mul_f32 v[0:1], v[52:53], v[0:1] op_sel:[1,0] op_sel_hi:[0,0]
	v_pk_fma_f32 v[8:9], v[52:53], v[2:3], v[0:1] neg_lo:[0,0,1] neg_hi:[0,0,1]
	v_pk_fma_f32 v[0:1], v[52:53], v[2:3], v[0:1] op_sel_hi:[1,0,1]
	s_nop 0
	v_mov_b32_e32 v9, v1
	s_waitcnt lgkmcnt(1)
	v_pk_add_f32 v[0:1], v[88:89], v[8:9]
	s_nop 0
	v_pk_mul_f32 v[2:3], v[52:53], v[0:1]
	v_pk_mul_f32 v[0:1], v[52:53], v[0:1] op_sel:[1,0] op_sel_hi:[0,1]
	v_sub_f32_e32 v2, v2, v3
	v_add_f32_e32 v0, v0, v1
	s_waitcnt lgkmcnt(0)
	v_add_f32_e32 v2, v90, v2
	v_add_f32_e32 v0, v91, v0
	v_pk_mul_f32 v[0:1], v[52:53], v[0:1] op_sel:[1,0] op_sel_hi:[0,0]
	v_pk_fma_f32 v[8:9], v[52:53], v[2:3], v[0:1] neg_lo:[0,0,1] neg_hi:[0,0,1]
	v_pk_fma_f32 v[0:1], v[52:53], v[2:3], v[0:1] op_sel_hi:[1,0,1]
	s_nop 0
	v_mov_b32_e32 v9, v1
	s_waitcnt lgkmcnt(1)
	v_pk_add_f32 v[0:1], v[92:93], v[8:9]
	s_nop 0
	v_pk_mul_f32 v[2:3], v[52:53], v[0:1]
	v_pk_mul_f32 v[0:1], v[52:53], v[0:1] op_sel:[1,0] op_sel_hi:[0,1]
	v_sub_f32_e32 v2, v2, v3
	v_add_f32_e32 v0, v0, v1
	s_waitcnt lgkmcnt(0)
	v_add_f32_e32 v2, v94, v2
	v_add_f32_e32 v0, v95, v0
	v_pk_mul_f32 v[0:1], v[52:53], v[0:1] op_sel:[1,0] op_sel_hi:[0,0]
	v_pk_fma_f32 v[8:9], v[52:53], v[2:3], v[0:1] neg_lo:[0,0,1] neg_hi:[0,0,1]
	v_pk_fma_f32 v[0:1], v[52:53], v[2:3], v[0:1] op_sel_hi:[1,0,1]
	s_nop 0
	v_mov_b32_e32 v9, v1
	s_waitcnt lgkmcnt(1)
	v_pk_add_f32 v[0:1], v[96:97], v[8:9]
	s_nop 0
	v_pk_mul_f32 v[2:3], v[52:53], v[0:1]
	v_pk_mul_f32 v[0:1], v[52:53], v[0:1] op_sel:[1,0] op_sel_hi:[0,1]
	v_sub_f32_e32 v2, v2, v3
	v_add_f32_e32 v0, v0, v1
	s_waitcnt lgkmcnt(0)
	v_add_f32_e32 v2, v98, v2
	v_add_f32_e32 v0, v99, v0
	v_pk_mul_f32 v[0:1], v[52:53], v[0:1] op_sel:[1,0] op_sel_hi:[0,0]
	v_pk_fma_f32 v[8:9], v[52:53], v[2:3], v[0:1] neg_lo:[0,0,1] neg_hi:[0,0,1]
	v_pk_fma_f32 v[0:1], v[52:53], v[2:3], v[0:1] op_sel_hi:[1,0,1]
	s_nop 0
	v_mov_b32_e32 v9, v1
	s_waitcnt lgkmcnt(1)
	v_pk_add_f32 v[0:1], v[100:101], v[8:9]
	s_nop 0
	v_pk_mul_f32 v[2:3], v[52:53], v[0:1]
	v_pk_mul_f32 v[0:1], v[52:53], v[0:1] op_sel:[1,0] op_sel_hi:[0,1]
	v_sub_f32_e32 v2, v2, v3
	v_add_f32_e32 v0, v0, v1
	s_waitcnt lgkmcnt(0)
	v_add_f32_e32 v2, v102, v2
	v_add_f32_e32 v0, v103, v0
	ds_read2st64_b32 v[6:7], v63 offset0:6 offset1:7
	v_pk_mul_f32 v[0:1], v[52:53], v[0:1] op_sel:[1,0] op_sel_hi:[0,0]
	v_pk_fma_f32 v[8:9], v[52:53], v[2:3], v[0:1] neg_lo:[0,0,1] neg_hi:[0,0,1]
	v_pk_fma_f32 v[0:1], v[52:53], v[2:3], v[0:1] op_sel_hi:[1,0,1]
	s_nop 0
	v_mov_b32_e32 v9, v1
	s_waitcnt lgkmcnt(1)
	v_pk_add_f32 v[0:1], v[104:105], v[8:9]
	s_nop 0
	v_pk_mul_f32 v[2:3], v[52:53], v[0:1]
	v_pk_mul_f32 v[0:1], v[52:53], v[0:1] op_sel:[1,0] op_sel_hi:[0,1]
	v_sub_f32_e32 v2, v2, v3
	v_add_f32_e32 v0, v0, v1
	s_waitcnt lgkmcnt(0)
	v_add_f32_e32 v2, v6, v2
	v_add_f32_e32 v0, v7, v0
	ds_read2st64_b32 v[4:5], v64 offset0:4 offset1:5
	ds_read2_b32 v[6:7], v50 offset0:132 offset1:196
	v_pk_mul_f32 v[0:1], v[52:53], v[0:1] op_sel:[1,0] op_sel_hi:[0,0]
	v_pk_fma_f32 v[8:9], v[52:53], v[2:3], v[0:1] neg_lo:[0,0,1] neg_hi:[0,0,1]
	v_pk_fma_f32 v[0:1], v[52:53], v[2:3], v[0:1] op_sel_hi:[1,0,1]
	s_nop 0
	v_mov_b32_e32 v9, v1
	s_waitcnt lgkmcnt(1)
	v_pk_add_f32 v[0:1], v[4:5], v[8:9]
	ds_read2st64_b32 v[4:5], v50 offset1:1
	v_pk_mul_f32 v[2:3], v[52:53], v[0:1]
	v_pk_mul_f32 v[0:1], v[52:53], v[0:1] op_sel:[1,0] op_sel_hi:[0,1]
	v_add_f32_e32 v0, v0, v1
	v_sub_f32_e32 v2, v2, v3
	s_waitcnt lgkmcnt(1)
	v_add_f32_e32 v0, v7, v0
	v_add_f32_e32 v2, v6, v2
	v_lshl_add_u64 v[6:7], v[48:49], 0, s[0:1]
	v_pk_mul_f32 v[0:1], v[52:53], v[0:1] op_sel:[1,0] op_sel_hi:[0,0]
	v_readlane_b32 s0, v251, 1
	s_waitcnt vmcnt(0) lgkmcnt(0)
	v_pk_fma_f32 v[8:9], v[52:53], v[2:3], v[0:1] neg_lo:[0,0,1] neg_hi:[0,0,1]
	v_pk_fma_f32 v[0:1], v[52:53], v[2:3], v[0:1] op_sel_hi:[1,0,1]
	s_add_i32 s3, s3, s0
	v_readlane_b32 s0, v255, 7
	v_mov_b32_e32 v9, v1
	s_add_i32 s2, s2, s0
	s_waitcnt lgkmcnt(0)
	v_pk_add_f32 v[0:1], v[4:5], v[8:9]
	s_cmpk_gt_i32 s3, 0x41f
	global_store_dwordx2 v[6:7], v[0:1], off
	v_readlane_b32 s1, v251, 2
	s_cbranch_scc1 .LBB0_1294

.LBB0_1326:
	s_or_b64 exec, exec, s[0:1]
	s_movk_i32 s0, 0x3200
	v_mul_lo_u32 v49, v60, s0
	v_and_or_b32 v48, v56, 63, v58
	v_add_u32_e32 v56, 0, v49
	v_lshl_add_u32 v54, v61, 2, v56
	s_waitcnt vmcnt(0) lgkmcnt(0)
	v_mfma_f32_16x16x32_bf16 v[64:67], v[44:47], v[8:11], 0
	v_mul_u32_u24_e32 v55, 0x210, v62
	v_lshlrev_b32_e32 v59, 2, v59
	v_lshlrev_b32_e32 v55, 2, v55
	v_mfma_f32_16x16x32_bf16 v[60:63], v[44:47], v[0:3], 0
	v_add3_u32 v55, v56, v59, v55
	v_add_u32_e32 v59, 0x400, v55
	s_nop 5
	ds_write2_b32 v55, v64, v60 offset1:16
	ds_write2_b32 v55, v65, v61 offset0:132 offset1:148
	ds_write2_b32 v59, v66, v62 offset0:8 offset1:24
	ds_write2_b32 v59, v67, v63 offset0:140 offset1:156
	v_mfma_f32_16x16x32_bf16 v[60:63], v[44:47], v[16:19], 0
	s_mulk_i32 s6, 0x108
	s_ashr_i32 s1, s6, 31
	s_ashr_i32 s7, s4, 31
	v_mfma_f32_16x16x32_bf16 v[64:67], v[44:47], v[4:7], 0
	s_nop 7
	ds_write2_b32 v55, v60, v64 offset0:32 offset1:48
	ds_write2_b32 v55, v61, v65 offset0:164 offset1:180
	ds_write2_b32 v59, v62, v66 offset0:40 offset1:56
	ds_write2_b32 v59, v63, v67 offset0:172 offset1:188
	v_mfma_f32_16x16x32_bf16 v[60:63], v[44:47], v[20:23], 0
	s_add_u32 s0, s6, s4
	v_ashrrev_i32_e32 v49, 31, v48
	s_addc_u32 s1, s1, s7
	v_mfma_f32_16x16x32_bf16 v[64:67], v[44:47], v[12:15], 0
	s_nop 7
	ds_write2_b32 v55, v60, v64 offset0:64 offset1:80
	ds_write2_b32 v55, v61, v65 offset0:196 offset1:212
	ds_write2_b32 v59, v62, v66 offset0:72 offset1:88
	ds_write2_b32 v59, v63, v67 offset0:204 offset1:220
	v_mfma_f32_16x16x32_bf16 v[60:63], v[44:47], v[28:31], 0
	v_lshl_add_u64 v[48:49], v[48:49], 3, s[58:59]
	s_lshl_b64 s[0:1], s[0:1], 14
	v_mfma_f32_16x16x32_bf16 v[44:47], v[44:47], v[24:27], 0
	s_nop 7
	ds_write2_b32 v55, v60, v44 offset0:96 offset1:112
	ds_write2_b32 v55, v61, v45 offset0:228 offset1:244
	ds_write2_b32 v59, v62, v46 offset0:104 offset1:120
	ds_write2_b32 v59, v63, v47 offset0:236 offset1:252
	s_waitcnt vmcnt(0) lgkmcnt(0)
	ds_read2st64_b32 v[44:45], v54 offset1:1
	ds_read2_b32 v[84:85], v54 offset0:132 offset1:196
	v_add_u32_e32 v86, 32, v54
	ds_read2st64_b32 v[88:89], v86 offset0:4 offset1:5
	v_add_u32_e32 v87, 48, v54
	ds_read2st64_b32 v[90:91], v87 offset0:6 offset1:7
	v_add_u32_e32 v92, 64, v54
	ds_read2st64_b32 v[94:95], v92 offset0:8 offset1:9
	v_add_u32_e32 v93, 0x50, v54
	ds_read2st64_b32 v[96:97], v93 offset0:10 offset1:11
	v_add_u32_e32 v98, 0x60, v54
	ds_read2st64_b32 v[100:101], v98 offset0:12 offset1:13
	v_add_u32_e32 v99, 0x70, v54
	ds_read2st64_b32 v[102:103], v99 offset0:14 offset1:15
	v_add_u32_e32 v104, 0x80, v54
	ds_read2st64_b32 v[106:107], v104 offset0:16 offset1:17
	v_add_u32_e32 v105, 0x90, v54
	ds_read2st64_b32 v[108:109], v105 offset0:18 offset1:19
	v_add_u32_e32 v110, 0xa0, v54
	ds_read2st64_b32 v[112:113], v110 offset0:20 offset1:21
	v_add_u32_e32 v111, 0xb0, v54
	ds_read2st64_b32 v[114:115], v111 offset0:22 offset1:23
	v_pk_mul_f32 v[46:47], v[52:53], 0 op_sel_hi:[1,0]
	v_sub_f32_e32 v60, v46, v47
	s_waitcnt lgkmcnt(1)
	v_add_f32_e32 v60, v60, v44
	v_add_f32_e32 v44, v46, v47
	v_add_f32_e32 v46, v44, v45
	v_add_u32_e32 v44, 32, v54
	v_pk_mul_f32 v[46:47], v[52:53], v[46:47] op_sel:[1,0] op_sel_hi:[0,0]
	v_pk_fma_f32 v[66:67], v[52:53], v[60:61], v[46:47] neg_lo:[0,0,1] neg_hi:[0,0,1]
	v_pk_fma_f32 v[46:47], v[52:53], v[60:61], v[46:47] op_sel_hi:[1,0,1]
	s_nop 0
	v_mov_b32_e32 v67, v47
	s_waitcnt lgkmcnt(1)
	v_pk_add_f32 v[46:47], v[84:85], v[66:67]
	s_nop 0
	v_pk_mul_f32 v[60:61], v[52:53], v[46:47]
	v_pk_mul_f32 v[46:47], v[52:53], v[46:47] op_sel:[1,0] op_sel_hi:[0,1]
	v_sub_f32_e32 v45, v60, v61
	s_waitcnt lgkmcnt(0)
	v_add_f32_e32 v60, v88, v45
	v_add_f32_e32 v45, v46, v47
	v_add_f32_e32 v62, v89, v45
	v_add_u32_e32 v45, 48, v54
	v_add_u32_e32 v46, 64, v54
	v_mov_b32_e32 v63, v85
	v_pk_mul_f32 v[62:63], v[52:53], v[62:63] op_sel:[1,0] op_sel_hi:[0,0]
	v_pk_fma_f32 v[68:69], v[52:53], v[60:61], v[62:63] neg_lo:[0,0,1] neg_hi:[0,0,1]
	v_pk_fma_f32 v[60:61], v[52:53], v[60:61], v[62:63] op_sel_hi:[1,0,1]
	s_nop 0
	v_mov_b32_e32 v69, v61
	s_waitcnt lgkmcnt(1)
	v_pk_add_f32 v[60:61], v[90:91], v[68:69]
	s_nop 0
	v_pk_mul_f32 v[62:63], v[52:53], v[60:61]
	v_pk_mul_f32 v[60:61], v[52:53], v[60:61] op_sel:[1,0] op_sel_hi:[0,1]
	v_sub_f32_e32 v47, v62, v63
	s_waitcnt lgkmcnt(0)
	v_add_f32_e32 v62, v94, v47
	v_add_f32_e32 v47, v60, v61
	v_add_f32_e32 v64, v95, v47
	v_add_u32_e32 v47, 0x50, v54
	v_add_u32_e32 v60, 0x60, v54
	v_mov_b32_e32 v65, v91
	v_pk_mul_f32 v[64:65], v[52:53], v[64:65] op_sel:[1,0] op_sel_hi:[0,0]
	v_pk_fma_f32 v[70:71], v[52:53], v[62:63], v[64:65] neg_lo:[0,0,1] neg_hi:[0,0,1]
	v_pk_fma_f32 v[62:63], v[52:53], v[62:63], v[64:65] op_sel_hi:[1,0,1]
	s_nop 0
	v_mov_b32_e32 v71, v63
	s_waitcnt lgkmcnt(1)
	v_pk_add_f32 v[62:63], v[96:97], v[70:71]
	s_nop 0
	v_pk_mul_f32 v[64:65], v[52:53], v[62:63]
	v_pk_mul_f32 v[62:63], v[52:53], v[62:63] op_sel:[1,0] op_sel_hi:[0,1]
	v_sub_f32_e32 v61, v64, v65
	s_waitcnt lgkmcnt(0)
	v_add_f32_e32 v64, v100, v61
	v_add_f32_e32 v61, v62, v63
	v_add_f32_e32 v66, v101, v61
	v_add_u32_e32 v61, 0x70, v54
	v_add_u32_e32 v62, 0x80, v54
	v_mov_b32_e32 v67, v97
	v_pk_mul_f32 v[66:67], v[52:53], v[66:67] op_sel:[1,0] op_sel_hi:[0,0]
	v_pk_fma_f32 v[72:73], v[52:53], v[64:65], v[66:67] neg_lo:[0,0,1] neg_hi:[0,0,1]
	v_pk_fma_f32 v[64:65], v[52:53], v[64:65], v[66:67] op_sel_hi:[1,0,1]
	s_nop 0
	v_mov_b32_e32 v73, v65
	s_waitcnt lgkmcnt(1)
	v_pk_add_f32 v[64:65], v[102:103], v[72:73]
	s_nop 0
	v_pk_mul_f32 v[66:67], v[52:53], v[64:65]
	v_pk_mul_f32 v[64:65], v[52:53], v[64:65] op_sel:[1,0] op_sel_hi:[0,1]
	v_sub_f32_e32 v63, v66, v67
	s_waitcnt lgkmcnt(0)
	v_add_f32_e32 v66, v106, v63
	v_add_f32_e32 v63, v64, v65
	v_add_f32_e32 v68, v107, v63
	v_add_u32_e32 v63, 0x90, v54
	v_add_u32_e32 v64, 0xa0, v54
	v_mov_b32_e32 v69, v103
	v_pk_mul_f32 v[68:69], v[52:53], v[68:69] op_sel:[1,0] op_sel_hi:[0,0]
	v_pk_fma_f32 v[74:75], v[52:53], v[66:67], v[68:69] neg_lo:[0,0,1] neg_hi:[0,0,1]
	v_pk_fma_f32 v[66:67], v[52:53], v[66:67], v[68:69] op_sel_hi:[1,0,1]
	s_nop 0
	v_mov_b32_e32 v75, v67
	s_waitcnt lgkmcnt(1)
	v_pk_add_f32 v[66:67], v[108:109], v[74:75]
	s_nop 0
	v_pk_mul_f32 v[68:69], v[52:53], v[66:67]
	v_pk_mul_f32 v[66:67], v[52:53], v[66:67] op_sel:[1,0] op_sel_hi:[0,1]
	v_sub_f32_e32 v65, v68, v69
	s_waitcnt lgkmcnt(0)
	v_add_f32_e32 v68, v112, v65
	v_add_f32_e32 v65, v66, v67
	v_add_f32_e32 v70, v113, v65
	v_add_u32_e32 v65, 0xb0, v54
	v_add_u32_e32 v66, 0xc0, v54
	v_mov_b32_e32 v71, v109
	v_pk_mul_f32 v[70:71], v[52:53], v[70:71] op_sel:[1,0] op_sel_hi:[0,0]
	ds_read2st64_b32 v[74:75], v66 offset0:24 offset1:25
	v_pk_fma_f32 v[76:77], v[52:53], v[68:69], v[70:71] neg_lo:[0,0,1] neg_hi:[0,0,1]
	v_pk_fma_f32 v[68:69], v[52:53], v[68:69], v[70:71] op_sel_hi:[1,0,1]
	s_nop 0
	v_mov_b32_e32 v77, v69
	s_waitcnt lgkmcnt(1)
	v_pk_add_f32 v[68:69], v[114:115], v[76:77]
	s_nop 0
	v_pk_mul_f32 v[70:71], v[52:53], v[68:69]
	v_pk_mul_f32 v[68:69], v[52:53], v[68:69] op_sel:[1,0] op_sel_hi:[0,1]
	v_sub_f32_e32 v67, v70, v71
	s_waitcnt lgkmcnt(0)
	v_add_f32_e32 v70, v74, v67
	v_add_f32_e32 v67, v68, v69
	v_add_f32_e32 v72, v75, v67
	v_add_u32_e32 v67, 0xd0, v54
	ds_read2st64_b32 v[74:75], v67 offset0:26 offset1:27
	v_add_u32_e32 v68, 0xe0, v54
	v_mov_b32_e32 v73, v115
	v_pk_mul_f32 v[72:73], v[52:53], v[72:73] op_sel:[1,0] op_sel_hi:[0,0]
	ds_read2st64_b32 v[76:77], v68 offset0:28 offset1:29
	v_pk_fma_f32 v[78:79], v[52:53], v[70:71], v[72:73] neg_lo:[0,0,1] neg_hi:[0,0,1]
	v_pk_fma_f32 v[70:71], v[52:53], v[70:71], v[72:73] op_sel_hi:[1,0,1]
	s_nop 0
	v_mov_b32_e32 v79, v71
	s_waitcnt lgkmcnt(1)
	v_pk_add_f32 v[70:71], v[74:75], v[78:79]
	s_nop 0
	v_pk_mul_f32 v[72:73], v[52:53], v[70:71]
	v_pk_mul_f32 v[70:71], v[52:53], v[70:71] op_sel:[1,0] op_sel_hi:[0,1]
	v_sub_f32_e32 v69, v72, v73
	s_waitcnt lgkmcnt(0)
	v_add_f32_e32 v78, v76, v69
	v_add_f32_e32 v69, v70, v71
	v_add_f32_e32 v80, v77, v69
	v_mfma_f32_16x16x32_bf16 v[70:73], v[40:43], v[8:11], 0
	v_add_u32_e32 v69, 0xf0, v54
	ds_read2st64_b32 v[82:83], v69 offset0:30 offset1:31
	s_waitcnt vmcnt(0) lgkmcnt(0)
	v_mfma_f32_16x16x32_bf16 v[74:77], v[40:43], v[0:3], 0
	s_nop 7
	ds_write2_b32 v55, v70, v74 offset1:16
	ds_write2_b32 v55, v71, v75 offset0:132 offset1:148
	ds_write2_b32 v59, v72, v76 offset0:8 offset1:24
	ds_write2_b32 v59, v73, v77 offset0:140 offset1:156
	v_mfma_f32_16x16x32_bf16 v[70:73], v[40:43], v[16:19], 0
	v_mfma_f32_16x16x32_bf16 v[74:77], v[40:43], v[4:7], 0
	s_nop 7
	ds_write2_b32 v55, v70, v74 offset0:32 offset1:48
	ds_write2_b32 v55, v71, v75 offset0:164 offset1:180
	ds_write2_b32 v59, v72, v76 offset0:40 offset1:56
	ds_write2_b32 v59, v73, v77 offset0:172 offset1:188
	v_mfma_f32_16x16x32_bf16 v[70:73], v[40:43], v[20:23], 0
	v_mfma_f32_16x16x32_bf16 v[74:77], v[40:43], v[12:15], 0
	s_nop 7
	ds_write2_b32 v55, v70, v74 offset0:64 offset1:80
	ds_write2_b32 v55, v71, v75 offset0:196 offset1:212
	ds_write2_b32 v59, v72, v76 offset0:72 offset1:88
	ds_write2_b32 v59, v73, v77 offset0:204 offset1:220
	v_mfma_f32_16x16x32_bf16 v[70:73], v[40:43], v[28:31], 0
	v_mfma_f32_16x16x32_bf16 v[40:43], v[40:43], v[24:27], 0
	s_nop 7
	ds_write2_b32 v55, v70, v40 offset0:96 offset1:112
	ds_write2_b32 v55, v71, v41 offset0:228 offset1:244
	ds_write2_b32 v59, v72, v42 offset0:104 offset1:120
	ds_write2_b32 v59, v73, v43 offset0:236 offset1:252
	v_pk_mul_f32 v[42:43], v[52:53], v[80:81] op_sel:[1,0] op_sel_hi:[0,0]
	s_waitcnt vmcnt(0) lgkmcnt(0)
	ds_read2st64_b32 v[40:41], v54 offset1:1
	ds_read2_b32 v[84:85], v54 offset0:132 offset1:196
	ds_read2st64_b32 v[86:87], v44 offset0:4 offset1:5
	ds_read2st64_b32 v[88:89], v45 offset0:6 offset1:7
	ds_read2st64_b32 v[90:91], v46 offset0:8 offset1:9
	ds_read2st64_b32 v[92:93], v47 offset0:10 offset1:11
	ds_read2st64_b32 v[94:95], v60 offset0:12 offset1:13
	ds_read2st64_b32 v[96:97], v61 offset0:14 offset1:15
	ds_read2st64_b32 v[98:99], v62 offset0:16 offset1:17
	ds_read2st64_b32 v[100:101], v63 offset0:18 offset1:19
	ds_read2st64_b32 v[102:103], v64 offset0:20 offset1:21
	ds_read2st64_b32 v[104:105], v65 offset0:22 offset1:23
	v_pk_fma_f32 v[70:71], v[52:53], v[78:79], v[42:43] neg_lo:[0,0,1] neg_hi:[0,0,1]
	v_pk_fma_f32 v[42:43], v[52:53], v[78:79], v[42:43] op_sel_hi:[1,0,1]
	s_nop 0
	v_mov_b32_e32 v71, v43
	s_waitcnt lgkmcnt(14)
	v_pk_add_f32 v[42:43], v[82:83], v[70:71]
	s_nop 0
	v_pk_mul_f32 v[70:71], v[52:53], v[42:43]
	v_pk_mul_f32 v[42:43], v[52:53], v[42:43] op_sel:[1,0] op_sel_hi:[0,1]
	v_sub_f32_e32 v70, v70, v71
	v_add_f32_e32 v42, v42, v43
	s_waitcnt lgkmcnt(0)
	v_add_f32_e32 v40, v70, v40
	v_add_f32_e32 v42, v42, v41
	v_pk_mul_f32 v[42:43], v[52:53], v[42:43] op_sel:[1,0] op_sel_hi:[0,0]
	v_pk_fma_f32 v[74:75], v[52:53], v[40:41], v[42:43] neg_lo:[0,0,1] neg_hi:[0,0,1]
	v_pk_fma_f32 v[40:41], v[52:53], v[40:41], v[42:43] op_sel_hi:[1,0,1]
	s_nop 0
	v_mov_b32_e32 v75, v41
	s_waitcnt lgkmcnt(1)
	v_pk_add_f32 v[40:41], v[84:85], v[74:75]
	s_nop 0
	v_pk_mul_f32 v[42:43], v[52:53], v[40:41]
	v_pk_mul_f32 v[40:41], v[52:53], v[40:41] op_sel:[1,0] op_sel_hi:[0,1]
	v_sub_f32_e32 v42, v42, v43
	v_add_f32_e32 v40, v40, v41
	s_waitcnt lgkmcnt(0)
	v_add_f32_e32 v42, v86, v42
	v_add_f32_e32 v40, v87, v40
	v_pk_mul_f32 v[40:41], v[52:53], v[40:41] op_sel:[1,0] op_sel_hi:[0,0]
	v_pk_fma_f32 v[74:75], v[52:53], v[42:43], v[40:41] neg_lo:[0,0,1] neg_hi:[0,0,1]
	v_pk_fma_f32 v[40:41], v[52:53], v[42:43], v[40:41] op_sel_hi:[1,0,1]
	s_nop 0
	v_mov_b32_e32 v75, v41
	s_waitcnt lgkmcnt(1)
	v_pk_add_f32 v[40:41], v[88:89], v[74:75]
	s_nop 0
	v_pk_mul_f32 v[42:43], v[52:53], v[40:41]
	v_pk_mul_f32 v[40:41], v[52:53], v[40:41] op_sel:[1,0] op_sel_hi:[0,1]
	v_sub_f32_e32 v42, v42, v43
	v_add_f32_e32 v40, v40, v41
	s_waitcnt lgkmcnt(0)
	v_add_f32_e32 v42, v90, v42
	v_add_f32_e32 v40, v91, v40
	v_pk_mul_f32 v[40:41], v[52:53], v[40:41] op_sel:[1,0] op_sel_hi:[0,0]
	v_pk_fma_f32 v[74:75], v[52:53], v[42:43], v[40:41] neg_lo:[0,0,1] neg_hi:[0,0,1]
	v_pk_fma_f32 v[40:41], v[52:53], v[42:43], v[40:41] op_sel_hi:[1,0,1]
	s_nop 0
	v_mov_b32_e32 v75, v41
	s_waitcnt lgkmcnt(1)
	v_pk_add_f32 v[40:41], v[92:93], v[74:75]
	s_nop 0
	v_pk_mul_f32 v[42:43], v[52:53], v[40:41]
	v_pk_mul_f32 v[40:41], v[52:53], v[40:41] op_sel:[1,0] op_sel_hi:[0,1]
	v_sub_f32_e32 v42, v42, v43
	v_add_f32_e32 v40, v40, v41
	s_waitcnt lgkmcnt(0)
	v_add_f32_e32 v42, v94, v42
	v_add_f32_e32 v40, v95, v40
	v_pk_mul_f32 v[40:41], v[52:53], v[40:41] op_sel:[1,0] op_sel_hi:[0,0]
	v_pk_fma_f32 v[74:75], v[52:53], v[42:43], v[40:41] neg_lo:[0,0,1] neg_hi:[0,0,1]
	v_pk_fma_f32 v[40:41], v[52:53], v[42:43], v[40:41] op_sel_hi:[1,0,1]
	s_nop 0
	v_mov_b32_e32 v75, v41
	s_waitcnt lgkmcnt(1)
	v_pk_add_f32 v[40:41], v[96:97], v[74:75]
	s_nop 0
	v_pk_mul_f32 v[42:43], v[52:53], v[40:41]
	v_pk_mul_f32 v[40:41], v[52:53], v[40:41] op_sel:[1,0] op_sel_hi:[0,1]
	v_sub_f32_e32 v42, v42, v43
	v_add_f32_e32 v40, v40, v41
	s_waitcnt lgkmcnt(0)
	v_add_f32_e32 v42, v98, v42
	v_add_f32_e32 v40, v99, v40
	v_pk_mul_f32 v[40:41], v[52:53], v[40:41] op_sel:[1,0] op_sel_hi:[0,0]
	v_pk_fma_f32 v[74:75], v[52:53], v[42:43], v[40:41] neg_lo:[0,0,1] neg_hi:[0,0,1]
	v_pk_fma_f32 v[40:41], v[52:53], v[42:43], v[40:41] op_sel_hi:[1,0,1]
	s_nop 0
	v_mov_b32_e32 v75, v41
	s_waitcnt lgkmcnt(1)
	v_pk_add_f32 v[40:41], v[100:101], v[74:75]
	s_nop 0
	v_pk_mul_f32 v[42:43], v[52:53], v[40:41]
	v_pk_mul_f32 v[40:41], v[52:53], v[40:41] op_sel:[1,0] op_sel_hi:[0,1]
	v_sub_f32_e32 v42, v42, v43
	v_add_f32_e32 v40, v40, v41
	s_waitcnt lgkmcnt(0)
	v_add_f32_e32 v42, v102, v42
	v_add_f32_e32 v40, v103, v40
	ds_read2st64_b32 v[72:73], v66 offset0:24 offset1:25
	v_pk_mul_f32 v[40:41], v[52:53], v[40:41] op_sel:[1,0] op_sel_hi:[0,0]
	v_pk_fma_f32 v[74:75], v[52:53], v[42:43], v[40:41] neg_lo:[0,0,1] neg_hi:[0,0,1]
	v_pk_fma_f32 v[40:41], v[52:53], v[42:43], v[40:41] op_sel_hi:[1,0,1]
	s_nop 0
	v_mov_b32_e32 v75, v41
	s_waitcnt lgkmcnt(1)
	v_pk_add_f32 v[40:41], v[104:105], v[74:75]
	s_nop 0
	v_pk_mul_f32 v[42:43], v[52:53], v[40:41]
	v_pk_mul_f32 v[40:41], v[52:53], v[40:41] op_sel:[1,0] op_sel_hi:[0,1]
	v_sub_f32_e32 v42, v42, v43
	v_add_f32_e32 v40, v40, v41
	s_waitcnt lgkmcnt(0)
	v_add_f32_e32 v42, v72, v42
	v_add_f32_e32 v40, v73, v40
	ds_read2st64_b32 v[70:71], v67 offset0:26 offset1:27
	ds_read2st64_b32 v[72:73], v68 offset0:28 offset1:29
	v_pk_mul_f32 v[40:41], v[52:53], v[40:41] op_sel:[1,0] op_sel_hi:[0,0]
	v_pk_fma_f32 v[74:75], v[52:53], v[42:43], v[40:41] neg_lo:[0,0,1] neg_hi:[0,0,1]
	v_pk_fma_f32 v[40:41], v[52:53], v[42:43], v[40:41] op_sel_hi:[1,0,1]
	ds_read2st64_b32 v[78:79], v69 offset0:30 offset1:31
	v_mov_b32_e32 v75, v41
	s_waitcnt lgkmcnt(2)
	v_pk_add_f32 v[40:41], v[70:71], v[74:75]
	s_waitcnt vmcnt(0) lgkmcnt(0)
	s_nop 0
	v_pk_mul_f32 v[42:43], v[52:53], v[40:41]
	v_pk_mul_f32 v[40:41], v[52:53], v[40:41] op_sel:[1,0] op_sel_hi:[0,1]
	v_sub_f32_e32 v42, v42, v43
	v_add_f32_e32 v40, v40, v41
	s_waitcnt lgkmcnt(1)
	v_add_f32_e32 v74, v72, v42
	v_add_f32_e32 v76, v73, v40
	v_mfma_f32_16x16x32_bf16 v[40:43], v[36:39], v[8:11], 0
	v_mfma_f32_16x16x32_bf16 v[70:73], v[36:39], v[0:3], 0
	s_nop 7
	ds_write2_b32 v55, v40, v70 offset1:16
	ds_write2_b32 v55, v41, v71 offset0:132 offset1:148
	ds_write2_b32 v59, v42, v72 offset0:8 offset1:24
	ds_write2_b32 v59, v43, v73 offset0:140 offset1:156
	v_mfma_f32_16x16x32_bf16 v[40:43], v[36:39], v[16:19], 0
	v_mfma_f32_16x16x32_bf16 v[70:73], v[36:39], v[4:7], 0
	s_nop 7
	ds_write2_b32 v55, v40, v70 offset0:32 offset1:48
	ds_write2_b32 v55, v41, v71 offset0:164 offset1:180
	ds_write2_b32 v59, v42, v72 offset0:40 offset1:56
	ds_write2_b32 v59, v43, v73 offset0:172 offset1:188
	v_mfma_f32_16x16x32_bf16 v[40:43], v[36:39], v[20:23], 0
	v_mfma_f32_16x16x32_bf16 v[70:73], v[36:39], v[12:15], 0
	s_nop 7
	ds_write2_b32 v55, v40, v70 offset0:64 offset1:80
	ds_write2_b32 v55, v41, v71 offset0:196 offset1:212
	ds_write2_b32 v59, v42, v72 offset0:72 offset1:88
	ds_write2_b32 v59, v43, v73 offset0:204 offset1:220
	v_mfma_f32_16x16x32_bf16 v[40:43], v[36:39], v[28:31], 0
	v_mfma_f32_16x16x32_bf16 v[36:39], v[36:39], v[24:27], 0
	s_nop 7
	ds_write2_b32 v55, v40, v36 offset0:96 offset1:112
	ds_write2_b32 v55, v41, v37 offset0:228 offset1:244
	ds_write2_b32 v59, v42, v38 offset0:104 offset1:120
	ds_write2_b32 v59, v43, v39 offset0:236 offset1:252
	v_pk_mul_f32 v[38:39], v[52:53], v[76:77] op_sel:[1,0] op_sel_hi:[0,0]
	s_waitcnt vmcnt(0) lgkmcnt(0)
	ds_read2st64_b32 v[36:37], v54 offset1:1
	ds_read2_b32 v[84:85], v54 offset0:132 offset1:196
	ds_read2st64_b32 v[86:87], v44 offset0:4 offset1:5
	ds_read2st64_b32 v[88:89], v45 offset0:6 offset1:7
	ds_read2st64_b32 v[90:91], v46 offset0:8 offset1:9
	ds_read2st64_b32 v[92:93], v47 offset0:10 offset1:11
	ds_read2st64_b32 v[94:95], v60 offset0:12 offset1:13
	ds_read2st64_b32 v[96:97], v61 offset0:14 offset1:15
	ds_read2st64_b32 v[98:99], v62 offset0:16 offset1:17
	ds_read2st64_b32 v[100:101], v63 offset0:18 offset1:19
	ds_read2st64_b32 v[102:103], v64 offset0:20 offset1:21
	ds_read2st64_b32 v[104:105], v65 offset0:22 offset1:23
	v_pk_fma_f32 v[40:41], v[52:53], v[74:75], v[38:39] neg_lo:[0,0,1] neg_hi:[0,0,1]
	v_pk_fma_f32 v[38:39], v[52:53], v[74:75], v[38:39] op_sel_hi:[1,0,1]
	v_mfma_f32_16x16x32_bf16 v[8:11], v[32:35], v[8:11], 0
	v_mov_b32_e32 v41, v39
	s_waitcnt lgkmcnt(14)
	v_pk_add_f32 v[38:39], v[78:79], v[40:41]
	s_nop 0
	v_pk_mul_f32 v[40:41], v[52:53], v[38:39]
	v_pk_mul_f32 v[38:39], v[52:53], v[38:39] op_sel:[1,0] op_sel_hi:[0,1]
	v_sub_f32_e32 v40, v40, v41
	v_add_f32_e32 v38, v38, v39
	s_waitcnt lgkmcnt(0)
	v_add_f32_e32 v36, v40, v36
	v_add_f32_e32 v38, v38, v37
	v_pk_mul_f32 v[38:39], v[52:53], v[38:39] op_sel:[1,0] op_sel_hi:[0,0]
	v_pk_fma_f32 v[70:71], v[52:53], v[36:37], v[38:39] neg_lo:[0,0,1] neg_hi:[0,0,1]
	v_pk_fma_f32 v[36:37], v[52:53], v[36:37], v[38:39] op_sel_hi:[1,0,1]
	v_mfma_f32_16x16x32_bf16 v[0:3], v[32:35], v[0:3], 0
	v_mov_b32_e32 v71, v37
	s_waitcnt lgkmcnt(1)
	v_pk_add_f32 v[36:37], v[84:85], v[70:71]
	s_nop 0
	v_pk_mul_f32 v[38:39], v[52:53], v[36:37]
	v_pk_mul_f32 v[36:37], v[52:53], v[36:37] op_sel:[1,0] op_sel_hi:[0,1]
	v_sub_f32_e32 v38, v38, v39
	v_add_f32_e32 v36, v36, v37
	s_waitcnt lgkmcnt(0)
	v_add_f32_e32 v38, v86, v38
	v_add_f32_e32 v36, v87, v36
	v_pk_mul_f32 v[36:37], v[52:53], v[36:37] op_sel:[1,0] op_sel_hi:[0,0]
	v_pk_fma_f32 v[70:71], v[52:53], v[38:39], v[36:37] neg_lo:[0,0,1] neg_hi:[0,0,1]
	v_pk_fma_f32 v[36:37], v[52:53], v[38:39], v[36:37] op_sel_hi:[1,0,1]
	v_mfma_f32_16x16x32_bf16 v[4:7], v[32:35], v[4:7], 0
	v_mov_b32_e32 v71, v37
	s_waitcnt lgkmcnt(1)
	v_pk_add_f32 v[36:37], v[88:89], v[70:71]
	s_nop 0
	v_pk_mul_f32 v[38:39], v[52:53], v[36:37]
	v_pk_mul_f32 v[36:37], v[52:53], v[36:37] op_sel:[1,0] op_sel_hi:[0,1]
	v_sub_f32_e32 v38, v38, v39
	v_add_f32_e32 v36, v36, v37
	s_waitcnt lgkmcnt(0)
	v_add_f32_e32 v38, v90, v38
	v_add_f32_e32 v36, v91, v36
	v_pk_mul_f32 v[36:37], v[52:53], v[36:37] op_sel:[1,0] op_sel_hi:[0,0]
	v_pk_fma_f32 v[70:71], v[52:53], v[38:39], v[36:37] neg_lo:[0,0,1] neg_hi:[0,0,1]
	v_pk_fma_f32 v[36:37], v[52:53], v[38:39], v[36:37] op_sel_hi:[1,0,1]
	s_nop 0
	v_mov_b32_e32 v71, v37
	s_waitcnt lgkmcnt(1)
	v_pk_add_f32 v[36:37], v[92:93], v[70:71]
	s_nop 0
	v_pk_mul_f32 v[38:39], v[52:53], v[36:37]
	v_pk_mul_f32 v[36:37], v[52:53], v[36:37] op_sel:[1,0] op_sel_hi:[0,1]
	v_sub_f32_e32 v38, v38, v39
	v_add_f32_e32 v36, v36, v37
	s_waitcnt lgkmcnt(0)
	v_add_f32_e32 v38, v94, v38
	v_add_f32_e32 v36, v95, v36
	v_pk_mul_f32 v[36:37], v[52:53], v[36:37] op_sel:[1,0] op_sel_hi:[0,0]
	v_pk_fma_f32 v[70:71], v[52:53], v[38:39], v[36:37] neg_lo:[0,0,1] neg_hi:[0,0,1]
	v_pk_fma_f32 v[36:37], v[52:53], v[38:39], v[36:37] op_sel_hi:[1,0,1]
	s_nop 0
	v_mov_b32_e32 v71, v37
	s_waitcnt lgkmcnt(1)
	v_pk_add_f32 v[36:37], v[96:97], v[70:71]
	s_nop 0
	v_pk_mul_f32 v[38:39], v[52:53], v[36:37]
	v_pk_mul_f32 v[36:37], v[52:53], v[36:37] op_sel:[1,0] op_sel_hi:[0,1]
	v_sub_f32_e32 v38, v38, v39
	v_add_f32_e32 v36, v36, v37
	s_waitcnt lgkmcnt(0)
	v_add_f32_e32 v38, v98, v38
	v_add_f32_e32 v36, v99, v36
	v_pk_mul_f32 v[36:37], v[52:53], v[36:37] op_sel:[1,0] op_sel_hi:[0,0]
	v_pk_fma_f32 v[70:71], v[52:53], v[38:39], v[36:37] neg_lo:[0,0,1] neg_hi:[0,0,1]
	v_pk_fma_f32 v[36:37], v[52:53], v[38:39], v[36:37] op_sel_hi:[1,0,1]
	s_nop 0
	v_mov_b32_e32 v71, v37
	s_waitcnt lgkmcnt(1)
	v_pk_add_f32 v[36:37], v[100:101], v[70:71]
	s_nop 0
	v_pk_mul_f32 v[38:39], v[52:53], v[36:37]
	v_pk_mul_f32 v[36:37], v[52:53], v[36:37] op_sel:[1,0] op_sel_hi:[0,1]
	v_sub_f32_e32 v38, v38, v39
	v_add_f32_e32 v36, v36, v37
	s_waitcnt lgkmcnt(0)
	v_add_f32_e32 v38, v102, v38
	v_add_f32_e32 v36, v103, v36
	ds_read2st64_b32 v[42:43], v66 offset0:24 offset1:25
	v_pk_mul_f32 v[36:37], v[52:53], v[36:37] op_sel:[1,0] op_sel_hi:[0,0]
	v_pk_fma_f32 v[70:71], v[52:53], v[38:39], v[36:37] neg_lo:[0,0,1] neg_hi:[0,0,1]
	v_pk_fma_f32 v[36:37], v[52:53], v[38:39], v[36:37] op_sel_hi:[1,0,1]
	s_nop 0
	v_mov_b32_e32 v71, v37
	s_waitcnt lgkmcnt(1)
	v_pk_add_f32 v[36:37], v[104:105], v[70:71]
	s_nop 0
	v_pk_mul_f32 v[38:39], v[52:53], v[36:37]
	v_pk_mul_f32 v[36:37], v[52:53], v[36:37] op_sel:[1,0] op_sel_hi:[0,1]
	v_sub_f32_e32 v38, v38, v39
	v_add_f32_e32 v36, v36, v37
	s_waitcnt lgkmcnt(0)
	v_add_f32_e32 v38, v42, v38
	v_add_f32_e32 v36, v43, v36
	ds_read2st64_b32 v[40:41], v67 offset0:26 offset1:27
	ds_read2st64_b32 v[42:43], v68 offset0:28 offset1:29
	v_pk_mul_f32 v[36:37], v[52:53], v[36:37] op_sel:[1,0] op_sel_hi:[0,0]
	v_pk_fma_f32 v[70:71], v[52:53], v[38:39], v[36:37] neg_lo:[0,0,1] neg_hi:[0,0,1]
	v_pk_fma_f32 v[36:37], v[52:53], v[38:39], v[36:37] op_sel_hi:[1,0,1]
	s_nop 0
	v_mov_b32_e32 v71, v37
	s_waitcnt lgkmcnt(1)
	v_pk_add_f32 v[36:37], v[40:41], v[70:71]
	ds_read2st64_b32 v[40:41], v69 offset0:30 offset1:31
	s_waitcnt vmcnt(0) lgkmcnt(0)
	ds_write2_b32 v55, v8, v0 offset1:16
	ds_write2_b32 v55, v9, v1 offset0:132 offset1:148
	ds_write2_b32 v59, v10, v2 offset0:8 offset1:24
	ds_write2_b32 v59, v11, v3 offset0:140 offset1:156
	v_mfma_f32_16x16x32_bf16 v[0:3], v[32:35], v[16:19], 0
	s_nop 7
	ds_write2_b32 v55, v0, v4 offset0:32 offset1:48
	ds_write2_b32 v55, v1, v5 offset0:164 offset1:180
	ds_write2_b32 v59, v2, v6 offset0:40 offset1:56
	ds_write2_b32 v59, v3, v7 offset0:172 offset1:188
	v_mfma_f32_16x16x32_bf16 v[0:3], v[32:35], v[20:23], 0
	v_mul_f32_e64 v38, v52, v36
	v_mul_f32_e64 v39, v53, v37
	v_pk_mul_f32 v[36:37], v[52:53], v[36:37] op_sel:[1,0] op_sel_hi:[0,1]
	v_add_f32_e32 v36, v36, v37
	v_mfma_f32_16x16x32_bf16 v[4:7], v[32:35], v[12:15], 0
	s_nop 7
	ds_write2_b32 v55, v0, v4 offset0:64 offset1:80
	ds_write2_b32 v55, v1, v5 offset0:196 offset1:212
	ds_write2_b32 v59, v2, v6 offset0:72 offset1:88
	ds_write2_b32 v59, v3, v7 offset0:204 offset1:220
	v_mfma_f32_16x16x32_bf16 v[0:3], v[32:35], v[28:31], 0
	v_sub_f32_e32 v38, v38, v39
	s_waitcnt lgkmcnt(13)
	v_add_f32_e32 v36, v43, v36
	v_add_f32_e32 v38, v42, v38
	v_mfma_f32_16x16x32_bf16 v[4:7], v[32:35], v[24:27], 0
	s_nop 7
	ds_write2_b32 v55, v0, v4 offset0:96 offset1:112
	ds_write2_b32 v55, v1, v5 offset0:228 offset1:244
	ds_write2_b32 v59, v2, v6 offset0:104 offset1:120
	ds_write2_b32 v59, v3, v7 offset0:236 offset1:252
	v_pk_mul_f32 v[2:3], v[52:53], v[36:37] op_sel:[1,0] op_sel_hi:[0,0]
	s_waitcnt vmcnt(0) lgkmcnt(0)
	ds_read2st64_b32 v[0:1], v54 offset1:1
	ds_read2_b32 v[84:85], v54 offset0:132 offset1:196
	ds_read2st64_b32 v[86:87], v44 offset0:4 offset1:5
	ds_read2st64_b32 v[88:89], v45 offset0:6 offset1:7
	ds_read2st64_b32 v[90:91], v46 offset0:8 offset1:9
	ds_read2st64_b32 v[92:93], v47 offset0:10 offset1:11
	ds_read2st64_b32 v[94:95], v60 offset0:12 offset1:13
	ds_read2st64_b32 v[96:97], v61 offset0:14 offset1:15
	ds_read2st64_b32 v[98:99], v62 offset0:16 offset1:17
	ds_read2st64_b32 v[100:101], v63 offset0:18 offset1:19
	ds_read2st64_b32 v[102:103], v64 offset0:20 offset1:21
	ds_read2st64_b32 v[104:105], v65 offset0:22 offset1:23
	v_pk_fma_f32 v[4:5], v[52:53], v[38:39], v[2:3] neg_lo:[0,0,1] neg_hi:[0,0,1]
	v_pk_fma_f32 v[2:3], v[52:53], v[38:39], v[2:3] op_sel_hi:[1,0,1]
	v_mov_b32_e32 v34, v207
	v_mov_b32_e32 v5, v3
	s_waitcnt lgkmcnt(14)
	v_pk_add_f32 v[2:3], v[40:41], v[4:5]
	v_mov_b32_e32 v10, 0
	v_pk_mul_f32 v[4:5], v[52:53], v[2:3]
	v_pk_mul_f32 v[2:3], v[52:53], v[2:3] op_sel:[1,0] op_sel_hi:[0,1]
	v_sub_f32_e32 v4, v4, v5
	v_add_f32_e32 v2, v2, v3
	s_waitcnt lgkmcnt(0)
	v_add_f32_e32 v0, v4, v0
	v_add_f32_e32 v2, v2, v1
	v_pk_mul_f32 v[2:3], v[52:53], v[2:3] op_sel:[1,0] op_sel_hi:[0,0]
	v_pk_fma_f32 v[8:9], v[52:53], v[0:1], v[2:3] neg_lo:[0,0,1] neg_hi:[0,0,1]
	v_pk_fma_f32 v[0:1], v[52:53], v[0:1], v[2:3] op_sel_hi:[1,0,1]
	v_mov_b32_e32 v11, 0
	v_mov_b32_e32 v9, v1
	s_waitcnt lgkmcnt(1)
	v_pk_add_f32 v[0:1], v[84:85], v[8:9]
	s_nop 0
	v_pk_mul_f32 v[2:3], v[52:53], v[0:1]
	v_pk_mul_f32 v[0:1], v[52:53], v[0:1] op_sel:[1,0] op_sel_hi:[0,1]
	v_sub_f32_e32 v2, v2, v3
	v_add_f32_e32 v0, v0, v1
	s_waitcnt lgkmcnt(0)
	v_add_f32_e32 v2, v86, v2
	v_add_f32_e32 v0, v87, v0
	v_pk_mul_f32 v[0:1], v[52:53], v[0:1] op_sel:[1,0] op_sel_hi:[0,0]
	v_pk_fma_f32 v[8:9], v[52:53], v[2:3], v[0:1] neg_lo:[0,0,1] neg_hi:[0,0,1]
	v_pk_fma_f32 v[0:1], v[52:53], v[2:3], v[0:1] op_sel_hi:[1,0,1]
	s_nop 0
	v_mov_b32_e32 v9, v1
	s_waitcnt lgkmcnt(1)
	v_pk_add_f32 v[0:1], v[88:89], v[8:9]
	s_nop 0
	v_pk_mul_f32 v[2:3], v[52:53], v[0:1]
	v_pk_mul_f32 v[0:1], v[52:53], v[0:1] op_sel:[1,0] op_sel_hi:[0,1]
	v_sub_f32_e32 v2, v2, v3
	v_add_f32_e32 v0, v0, v1
	s_waitcnt lgkmcnt(0)
	v_add_f32_e32 v2, v90, v2
	v_add_f32_e32 v0, v91, v0
	v_pk_mul_f32 v[0:1], v[52:53], v[0:1] op_sel:[1,0] op_sel_hi:[0,0]
	v_pk_fma_f32 v[8:9], v[52:53], v[2:3], v[0:1] neg_lo:[0,0,1] neg_hi:[0,0,1]
	v_pk_fma_f32 v[0:1], v[52:53], v[2:3], v[0:1] op_sel_hi:[1,0,1]
	s_nop 0
	v_mov_b32_e32 v9, v1
	s_waitcnt lgkmcnt(1)
	v_pk_add_f32 v[0:1], v[92:93], v[8:9]
	s_nop 0
	v_pk_mul_f32 v[2:3], v[52:53], v[0:1]
	v_pk_mul_f32 v[0:1], v[52:53], v[0:1] op_sel:[1,0] op_sel_hi:[0,1]
	v_sub_f32_e32 v2, v2, v3
	v_add_f32_e32 v0, v0, v1
	s_waitcnt lgkmcnt(0)
	v_add_f32_e32 v2, v94, v2
	v_add_f32_e32 v0, v95, v0
	v_pk_mul_f32 v[0:1], v[52:53], v[0:1] op_sel:[1,0] op_sel_hi:[0,0]
	v_pk_fma_f32 v[8:9], v[52:53], v[2:3], v[0:1] neg_lo:[0,0,1] neg_hi:[0,0,1]
	v_pk_fma_f32 v[0:1], v[52:53], v[2:3], v[0:1] op_sel_hi:[1,0,1]
	s_nop 0
	v_mov_b32_e32 v9, v1
	s_waitcnt lgkmcnt(1)
	v_pk_add_f32 v[0:1], v[96:97], v[8:9]
	s_nop 0
	v_pk_mul_f32 v[2:3], v[52:53], v[0:1]
	v_pk_mul_f32 v[0:1], v[52:53], v[0:1] op_sel:[1,0] op_sel_hi:[0,1]
	v_sub_f32_e32 v2, v2, v3
	v_add_f32_e32 v0, v0, v1
	s_waitcnt lgkmcnt(0)
	v_add_f32_e32 v2, v98, v2
	v_add_f32_e32 v0, v99, v0
	v_pk_mul_f32 v[0:1], v[52:53], v[0:1] op_sel:[1,0] op_sel_hi:[0,0]
	v_pk_fma_f32 v[8:9], v[52:53], v[2:3], v[0:1] neg_lo:[0,0,1] neg_hi:[0,0,1]
	v_pk_fma_f32 v[0:1], v[52:53], v[2:3], v[0:1] op_sel_hi:[1,0,1]
	s_nop 0
	v_mov_b32_e32 v9, v1
	s_waitcnt lgkmcnt(1)
	v_pk_add_f32 v[0:1], v[100:101], v[8:9]
	s_nop 0
	v_pk_mul_f32 v[2:3], v[52:53], v[0:1]
	v_pk_mul_f32 v[0:1], v[52:53], v[0:1] op_sel:[1,0] op_sel_hi:[0,1]
	v_sub_f32_e32 v2, v2, v3
	v_add_f32_e32 v0, v0, v1
	s_waitcnt lgkmcnt(0)
	v_add_f32_e32 v2, v102, v2
	v_add_f32_e32 v0, v103, v0
	ds_read2st64_b32 v[6:7], v66 offset0:24 offset1:25
	v_pk_mul_f32 v[0:1], v[52:53], v[0:1] op_sel:[1,0] op_sel_hi:[0,0]
	v_pk_fma_f32 v[8:9], v[52:53], v[2:3], v[0:1] neg_lo:[0,0,1] neg_hi:[0,0,1]
	v_pk_fma_f32 v[0:1], v[52:53], v[2:3], v[0:1] op_sel_hi:[1,0,1]
	s_nop 0
	v_mov_b32_e32 v9, v1
	s_waitcnt lgkmcnt(1)
	v_pk_add_f32 v[0:1], v[104:105], v[8:9]
	s_nop 0
	v_pk_mul_f32 v[2:3], v[52:53], v[0:1]
	v_pk_mul_f32 v[0:1], v[52:53], v[0:1] op_sel:[1,0] op_sel_hi:[0,1]
	v_sub_f32_e32 v2, v2, v3
	v_add_f32_e32 v0, v0, v1
	s_waitcnt lgkmcnt(0)
	v_add_f32_e32 v2, v6, v2
	v_add_f32_e32 v0, v7, v0
	ds_read2st64_b32 v[4:5], v67 offset0:26 offset1:27
	ds_read2st64_b32 v[6:7], v68 offset0:28 offset1:29
	v_pk_mul_f32 v[0:1], v[52:53], v[0:1] op_sel:[1,0] op_sel_hi:[0,0]
	v_pk_fma_f32 v[8:9], v[52:53], v[2:3], v[0:1] neg_lo:[0,0,1] neg_hi:[0,0,1]
	v_pk_fma_f32 v[0:1], v[52:53], v[2:3], v[0:1] op_sel_hi:[1,0,1]
	s_nop 0
	v_mov_b32_e32 v9, v1
	s_waitcnt lgkmcnt(1)
	v_pk_add_f32 v[0:1], v[4:5], v[8:9]
	ds_read2st64_b32 v[4:5], v69 offset0:30 offset1:31
	v_pk_mul_f32 v[2:3], v[52:53], v[0:1]
	v_pk_mul_f32 v[0:1], v[52:53], v[0:1] op_sel:[1,0] op_sel_hi:[0,1]
	v_add_f32_e32 v0, v0, v1
	v_sub_f32_e32 v2, v2, v3
	s_waitcnt lgkmcnt(1)
	v_add_f32_e32 v0, v7, v0
	v_add_f32_e32 v2, v6, v2
	v_pk_mul_f32 v[0:1], v[52:53], v[0:1] op_sel:[1,0] op_sel_hi:[0,0]
	v_pk_fma_f32 v[8:9], v[52:53], v[2:3], v[0:1] neg_lo:[0,0,1] neg_hi:[0,0,1]
	v_pk_fma_f32 v[0:1], v[52:53], v[2:3], v[0:1] op_sel_hi:[1,0,1]
	v_lshl_add_u64 v[6:7], v[48:49], 0, s[0:1]
	v_mov_b32_e32 v9, v1
	s_waitcnt lgkmcnt(0)
	v_pk_add_f32 v[0:1], v[4:5], v[8:9]
	s_waitcnt vmcnt(0) lgkmcnt(0)
	global_store_dwordx2 v[6:7], v[0:1], off
	v_add_u32_e32 v0, s90, v58
	v_and_b32_e32 v60, 63, v34
	v_or_b32_e32 v0, v60, v0
	v_ashrrev_i32_e32 v1, 31, v0
	v_lshl_add_u64 v[0:1], v[0:1], 3, s[60:61]
	global_load_dwordx2 v[52:53], v[0:1], off
	v_add_u32_e32 v0, s91, v57
	v_ashrrev_i32_e32 v1, 31, v0
	v_and_b32_e32 v59, 15, v34
	v_lshlrev_b64 v[0:1], 12, v[0:1]
	v_lshl_add_u64 v[0:1], s[62:63], 0, v[0:1]
	v_lshlrev_b32_e32 v2, 4, v59
	v_and_b32_e32 v128, 48, v34
	v_cmp_gt_u32_e64 s[44:45], 32, v60
	v_lshl_add_u64 v[32:33], v[0:1], 0, v[128:129]
	v_mov_b32_e32 v0, 0
	v_lshlrev_b32_e32 v128, 1, v2
	v_mov_b32_e32 v8, 0
	v_mov_b32_e32 v9, 0
	s_and_saveexec_b64 s[0:1], s[44:45]
	s_cbranch_execz .LBB0_1328
	v_lshl_add_u64 v[2:3], v[32:33], 0, v[128:129]
	global_load_dwordx4 v[8:11], v[2:3], off
